# prep transposes: nt cache policy on the once-read f32 weight loads
# baseline (speedup 1.0000x reference)
; __device__ __forceinline__ void xpose_load(const XpItem& x, int lane, f32x4 (&v)[8]) {
; #pragma unroll
;     for (int i = 0; i < 8; ++i) v[i] = *(const f32x4*)(x.src + (size_t)(x.k0 + 8 * i + (lane >> 3)) * x.N + x.n0 + (lane & 7) * 4);
; }
; __device__ __forceinline__ void phase_prep(CParams& p, int layer, LAS unsigned char* lds) {
;     ...
;         XpItem cur, nxt; f32x4 vc[8], vn[8];
;         int it = gw;
;         if (it < NIT) { decode(it, cur); xpose_load(cur, lane, vc); }
.LBB0_74:
	s_or_b64 exec, exec, s[14:15]
	v_lshrrev_b32_e32 v78, 3, v36
	v_add_u32_e32 v5, v0, v78
	v_ashrrev_i32_e32 v6, 31, v5
	v_mul_lo_u32 v8, v30, v6
	v_mul_lo_u32 v9, v31, v5
	v_mad_u64_u32 v[6:7], s[8:9], v30, v5, 0
	v_or_b32_e32 v80, 16, v78
	v_or_b32_e32 v82, 32, v78
	v_or_b32_e32 v84, 48, v78
	v_add3_u32 v7, v7, v8, v9
	v_ashrrev_i32_e32 v5, 31, v4
	v_add_u32_e32 v12, v0, v80
	v_add_u32_e32 v20, v0, v82
	v_add_u32_e32 v34, v0, v84
	v_lshl_add_u64 v[6:7], v[6:7], 2, v[28:29]
	v_lshlrev_b64 v[32:33], 2, v[4:5]
	v_ashrrev_i32_e32 v13, 31, v12
	v_ashrrev_i32_e32 v21, 31, v20
	v_ashrrev_i32_e32 v35, 31, v34
	v_lshl_add_u64 v[4:5], v[6:7], 0, v[32:33]
	v_lshlrev_b32_e32 v6, 2, v36
	v_or_b32_e32 v79, 8, v78
	v_mul_lo_u32 v14, v30, v13
	v_mul_lo_u32 v15, v31, v12
	v_mad_u64_u32 v[12:13], s[8:9], v30, v12, 0
	v_or_b32_e32 v81, 24, v78
	v_mul_lo_u32 v22, v30, v21
	v_mul_lo_u32 v23, v31, v20
	v_mad_u64_u32 v[20:21], s[8:9], v30, v20, 0
	v_or_b32_e32 v83, 40, v78
	v_mul_lo_u32 v37, v30, v35
	v_mul_lo_u32 v39, v31, v34
	v_mad_u64_u32 v[34:35], s[8:9], v30, v34, 0
	v_or_b32_e32 v85, 56, v78
	v_and_b32_e32 v38, 28, v6
	v_add_u32_e32 v6, v0, v79
	v_add3_u32 v13, v13, v14, v15
	v_add_u32_e32 v14, v0, v81
	v_add3_u32 v21, v21, v22, v23
	v_add_u32_e32 v22, v0, v83
	v_add3_u32 v35, v35, v37, v39
	v_add_u32_e32 v37, v0, v85
	v_ashrrev_i32_e32 v7, 31, v6
	v_ashrrev_i32_e32 v15, 31, v14
	v_ashrrev_i32_e32 v23, 31, v22
	v_ashrrev_i32_e32 v39, 31, v37
	v_mul_lo_u32 v8, v30, v7
	v_mul_lo_u32 v9, v31, v6
	v_mad_u64_u32 v[6:7], s[8:9], v30, v6, 0
	v_mul_lo_u32 v16, v30, v15
	v_mul_lo_u32 v17, v31, v14
	v_mad_u64_u32 v[14:15], s[8:9], v30, v14, 0
	v_mul_lo_u32 v24, v30, v23
	v_mul_lo_u32 v25, v31, v22
	v_mad_u64_u32 v[22:23], s[8:9], v30, v22, 0
	v_mul_lo_u32 v39, v30, v39
	v_mul_lo_u32 v42, v31, v37
	v_mad_u64_u32 v[30:31], s[8:9], v30, v37, 0
	v_add3_u32 v7, v7, v8, v9
	v_add3_u32 v15, v15, v16, v17
	v_add3_u32 v23, v23, v24, v25
	v_add3_u32 v31, v31, v39, v42
	v_lshl_add_u64 v[6:7], v[6:7], 2, v[28:29]
	v_lshl_add_u64 v[12:13], v[12:13], 2, v[28:29]
	v_lshl_add_u64 v[14:15], v[14:15], 2, v[28:29]
	v_lshl_add_u64 v[20:21], v[20:21], 2, v[28:29]
	v_lshl_add_u64 v[22:23], v[22:23], 2, v[28:29]
	v_lshl_add_u64 v[34:35], v[34:35], 2, v[28:29]
	v_lshl_add_u64 v[28:29], v[30:31], 2, v[28:29]
	v_lshlrev_b32_e32 v40, 2, v38
	v_mov_b32_e32 v41, v2
	v_lshl_add_u64 v[6:7], v[6:7], 0, v[32:33]
	v_lshl_add_u64 v[12:13], v[12:13], 0, v[32:33]
	v_lshl_add_u64 v[14:15], v[14:15], 0, v[32:33]
	v_lshl_add_u64 v[20:21], v[20:21], 0, v[32:33]
	v_lshl_add_u64 v[22:23], v[22:23], 0, v[32:33]
	v_lshl_add_u64 v[34:35], v[34:35], 0, v[32:33]
	v_lshl_add_u64 v[28:29], v[28:29], 0, v[32:33]
	v_lshl_add_u64 v[4:5], v[4:5], 0, v[40:41]
	v_lshl_add_u64 v[8:9], v[6:7], 0, v[40:41]
	v_lshl_add_u64 v[12:13], v[12:13], 0, v[40:41]
	v_lshl_add_u64 v[16:17], v[14:15], 0, v[40:41]
	v_lshl_add_u64 v[20:21], v[20:21], 0, v[40:41]
	v_lshl_add_u64 v[24:25], v[22:23], 0, v[40:41]
	v_lshl_add_u64 v[34:35], v[34:35], 0, v[40:41]
	v_lshl_add_u64 v[32:33], v[28:29], 0, v[40:41]
	global_load_dwordx4 v[4:7], v[4:5], off nt
	s_nop 0
	global_load_dwordx4 v[8:11], v[8:9], off nt
	s_nop 0
	global_load_dwordx4 v[12:15], v[12:13], off nt
	s_nop 0
	global_load_dwordx4 v[16:19], v[16:17], off nt
	s_nop 0
	global_load_dwordx4 v[20:23], v[20:21], off nt
	s_nop 0
	global_load_dwordx4 v[24:27], v[24:25], off nt
	s_nop 0
	global_load_dwordx4 v[28:31], v[34:35], off nt
	s_nop 0
	global_load_dwordx4 v[32:35], v[32:33], off nt
	s_load_dwordx2 s[8:9], s[60:61], 0xd0
	v_readlane_b32 s10, v255, 40
	v_readlane_b32 s11, v255, 41
	s_load_dwordx2 s[14:15], s[60:61], 0x20
	s_movk_i32 s6, 0x2100
	s_waitcnt lgkmcnt(0)
	s_add_u32 s48, s8, s10
	s_addc_u32 s49, s9, 0
	s_load_dwordx4 s[8:11], s[60:61], 0xb0
	s_add_u32 s50, s4, 0x17c00000
	s_addc_u32 s51, s5, 0
	s_add_u32 s62, s4, 0x15000000
	s_addc_u32 s63, s5, 0
	s_waitcnt lgkmcnt(0)
	s_add_u32 s64, s10, s59
	s_addc_u32 s65, s11, 0
	s_add_u32 s66, s4, 0x14800000
	s_addc_u32 s67, s5, 0
	s_add_u32 s68, s8, s59
	s_addc_u32 s69, s9, 0
	s_add_u32 s70, s4, 0x14000000
	s_addc_u32 s71, s5, 0
	s_add_u32 s72, s14, s39
	v_mul_lo_u32 v37, v1, s6
	s_addc_u32 s73, s15, 0
	v_lshlrev_b32_e32 v36, 3, v36
	v_add_u32_e32 v37, 0, v37
	s_add_u32 s74, s4, 0x10400000
	v_and_b32_e32 v36, 56, v36
	v_readlane_b32 s6, v253, 9
	s_addc_u32 s75, s5, 0
	v_add_u32_e32 v39, v37, v40
	v_mul_u32_u24_e32 v40, 0x84, v78
	v_mul_u32_u24_e32 v41, 0x84, v36
	v_lshlrev_b32_e32 v42, 2, v78
	s_add_i32 s6, s6, s28
	v_add3_u32 v86, v37, v41, v42
	v_add_lshl_u32 v87, s6, v1, 5
	s_lshl_b32 s6, s28, 5
	s_mov_b64 s[76:77], 0
	v_lshlrev_b32_e32 v70, 2, v38
	v_add_u32_e32 v88, v39, v40
	v_lshlrev_b32_e32 v72, 1, v36
	s_branch .LBB0_76

; __device__ __forceinline__ void xpose_load(const XpItem& x, int lane, f32x4 (&v)[8]) {
; #pragma unroll
;     for (int i = 0; i < 8; ++i) v[i] = *(const f32x4*)(x.src + (size_t)(x.k0 + 8 * i + (lane >> 3)) * x.N + x.n0 + (lane & 7) * 4);
; }
; __device__ __forceinline__ void phase_prep(CParams& p, int layer, LAS unsigned char* lds) {
;     ...
;         for (; it < NIT; it += NW) {
;             const bool hn = (it + NW) < NIT;
;             if (hn) { decode(it + NW, nxt); xpose_load(nxt, lane, vn); }
.LBB0_93:
	s_or_b64 exec, exec, s[14:15]
	v_add_u32_e32 v1, v89, v78
	v_ashrrev_i32_e32 v37, 31, v1
	v_mul_lo_u32 v37, v60, v37
	v_mul_lo_u32 v40, v61, v1
	v_mad_u64_u32 v[38:39], s[8:9], v60, v1, 0
	v_add3_u32 v39, v39, v37, v40
	v_ashrrev_i32_e32 v37, 31, v36
	v_lshl_add_u64 v[38:39], v[38:39], 2, v[62:63]
	v_lshlrev_b64 v[64:65], 2, v[36:37]
	v_add_u32_e32 v1, v89, v79
	v_lshl_add_u64 v[36:37], v[38:39], 0, v[64:65]
	v_ashrrev_i32_e32 v38, 31, v1
	v_mul_lo_u32 v40, v60, v38
	v_mul_lo_u32 v41, v61, v1
	v_mad_u64_u32 v[38:39], s[8:9], v60, v1, 0
	v_add_u32_e32 v1, v89, v80
	v_ashrrev_i32_e32 v44, 31, v1
	v_mul_lo_u32 v46, v60, v44
	v_mul_lo_u32 v47, v61, v1
	v_mad_u64_u32 v[44:45], s[8:9], v60, v1, 0
	v_add_u32_e32 v1, v89, v81
	v_add3_u32 v45, v45, v46, v47
	v_ashrrev_i32_e32 v46, 31, v1
	v_mul_lo_u32 v48, v60, v46
	v_mul_lo_u32 v49, v61, v1
	v_mad_u64_u32 v[46:47], s[8:9], v60, v1, 0
	v_add_u32_e32 v1, v89, v82
	v_ashrrev_i32_e32 v52, 31, v1
	v_mul_lo_u32 v54, v60, v52
	v_mul_lo_u32 v55, v61, v1
	v_mad_u64_u32 v[52:53], s[8:9], v60, v1, 0
	v_add_u32_e32 v1, v89, v83
	v_add3_u32 v53, v53, v54, v55
	v_ashrrev_i32_e32 v54, 31, v1
	v_mul_lo_u32 v56, v60, v54
	v_mul_lo_u32 v57, v61, v1
	v_mad_u64_u32 v[54:55], s[8:9], v60, v1, 0
	v_add_u32_e32 v1, v89, v84
	v_ashrrev_i32_e32 v66, 31, v1
	v_mul_lo_u32 v73, v60, v66
	v_mul_lo_u32 v92, v61, v1
	v_mad_u64_u32 v[66:67], s[8:9], v60, v1, 0
	v_add_u32_e32 v1, v89, v85
	v_add3_u32 v67, v67, v73, v92
	v_ashrrev_i32_e32 v73, 31, v1
	v_mul_lo_u32 v73, v60, v73
	v_mul_lo_u32 v92, v61, v1
	v_mad_u64_u32 v[60:61], s[8:9], v60, v1, 0
	v_add3_u32 v39, v39, v40, v41
	v_add3_u32 v47, v47, v48, v49
	v_add3_u32 v55, v55, v56, v57
	v_add3_u32 v61, v61, v73, v92
	v_lshl_add_u64 v[38:39], v[38:39], 2, v[62:63]
	v_lshl_add_u64 v[44:45], v[44:45], 2, v[62:63]
	v_lshl_add_u64 v[46:47], v[46:47], 2, v[62:63]
	v_lshl_add_u64 v[52:53], v[52:53], 2, v[62:63]
	v_lshl_add_u64 v[54:55], v[54:55], 2, v[62:63]
	v_lshl_add_u64 v[66:67], v[66:67], 2, v[62:63]
	v_lshl_add_u64 v[60:61], v[60:61], 2, v[62:63]
	v_mov_b32_e32 v71, v2
	v_lshl_add_u64 v[38:39], v[38:39], 0, v[64:65]
	v_lshl_add_u64 v[44:45], v[44:45], 0, v[64:65]
	v_lshl_add_u64 v[46:47], v[46:47], 0, v[64:65]
	v_lshl_add_u64 v[52:53], v[52:53], 0, v[64:65]
	v_lshl_add_u64 v[54:55], v[54:55], 0, v[64:65]
	v_lshl_add_u64 v[66:67], v[66:67], 0, v[64:65]
	v_lshl_add_u64 v[60:61], v[60:61], 0, v[64:65]
	v_lshl_add_u64 v[36:37], v[36:37], 0, v[70:71]
	v_lshl_add_u64 v[38:39], v[38:39], 0, v[70:71]
	v_lshl_add_u64 v[44:45], v[44:45], 0, v[70:71]
	v_lshl_add_u64 v[46:47], v[46:47], 0, v[70:71]
	v_lshl_add_u64 v[52:53], v[52:53], 0, v[70:71]
	v_lshl_add_u64 v[54:55], v[54:55], 0, v[70:71]
	v_lshl_add_u64 v[66:67], v[66:67], 0, v[70:71]
	v_lshl_add_u64 v[60:61], v[60:61], 0, v[70:71]
	global_load_dwordx4 v[40:43], v[36:37], off nt
	s_nop 0
	global_load_dwordx4 v[36:39], v[38:39], off nt
	s_nop 0
	global_load_dwordx4 v[48:51], v[44:45], off nt
	s_nop 0
	global_load_dwordx4 v[44:47], v[46:47], off nt
	s_nop 0
	global_load_dwordx4 v[56:59], v[52:53], off nt
	s_nop 0
	global_load_dwordx4 v[52:55], v[54:55], off nt
	s_nop 0
	global_load_dwordx4 v[64:67], v[66:67], off nt
	s_nop 0
	global_load_dwordx4 v[60:63], v[60:61], off nt
